# STORE-TAIL: attention end-of-unit barrier no longer waits for the unit's output stores (lgkmcnt only; vmcnt is in issue order so the next unit's counted waits still hold), on ACQ-HOIST
# speedup vs baseline: 1.0057x; 1.0057x over previous
.LBB0_972:
	s_waitcnt lgkmcnt(0)
	s_barrier
	s_add_i32 s40, s40, s73
	s_cmpk_lt_i32 s40, 0x500
	s_cbranch_scc0 .LBB0_993
